# v56: v50 + P2 K-loop head at 16 mod 64 (+28 B) with the scan-exit pad shrunk to 8 B so P5/P7/P8 keep v54's absolute addresses
# baseline (speedup 1.0000x reference)
; __device__ __forceinline__ void xcd_barrier(const XcdBarrier& b) {
;     asm volatile("s_waitcnt vmcnt(0)" ::: "memory");
;     __syncthreads();
;     if (threadIdx.x == 0) {
;         unsigned* bar = b.bar;
;         __builtin_amdgcn_s_waitcnt(0);
;         unsigned nloc = b.st[0], nx = b.st[1];
;         if (nloc == 0u) { xcd_barrier_complete(bar, b.x, nloc, nx); b.st[0] = nloc; b.st[1] = nx; }
; __device__ __forceinline__ void p3_gla_scan(LAS unsigned char* lds_, const Params& p) {
;     ...
;         asm volatile("s_waitcnt vmcnt(0)" ::: "memory");
;     ...
;     }
;     __syncthreads();
.LBB0_628:
	s_nop 0
	s_nop 0
	s_waitcnt lgkmcnt(0)
	s_barrier
	s_waitcnt vmcnt(0)
	s_barrier
	s_and_saveexec_b64 s[0:1], s[50:51]
	v_readlane_b32 s72, v247, 25
	v_readlane_b32 s76, v247, 21
	v_readlane_b32 s73, v247, 26
	v_readlane_b32 s77, v247, 22
	s_cbranch_execz .LBB0_680
	s_add_i32 s4, 0, 0x26020
	v_mov_b32_e32 v1, s4
	s_waitcnt vmcnt(0) expcnt(0) lgkmcnt(0)
	ds_read_b32 v3, v1
	s_add_i32 s4, 0, 0x26024
	v_mov_b32_e32 v1, s4
	ds_read_b32 v1, v1
	s_waitcnt lgkmcnt(1)
	v_cmp_ne_u32_e32 vcc, 0, v3
	s_cbranch_vccnz .LBB0_644
	v_readlane_b32 s4, v247, 0
	v_readlane_b32 s5, v247, 1
	s_load_dwordx2 s[8:9], s[4:5], 0x4
	s_add_u32 s4, s96, 0x4200
	s_addc_u32 s5, s97, 0
	s_add_u32 s6, s96, 0x4400
	s_addc_u32 s7, s97, 0
	s_waitcnt lgkmcnt(0)
	s_mul_i32 s33, s8, s60
	s_add_u32 s8, s96, 0x4500
	s_mul_i32 s33, s33, s9
	s_addc_u32 s9, s97, 0
	s_add_u32 s10, s96, 0x4600
	s_addc_u32 s11, s97, 0
	s_add_u32 s12, s96, 0x4700
	s_addc_u32 s13, s97, 0
	s_add_u32 s14, s96, 0x4800
	s_addc_u32 s15, s97, 0
	s_add_u32 s16, s96, 0x4900
	s_addc_u32 s17, s97, 0
	s_add_u32 s18, s96, 0x4a00
	s_addc_u32 s19, s97, 0
	s_add_u32 s20, s96, 0x4b00
	s_addc_u32 s21, s97, 0
	s_add_u32 s22, s96, 0x4c00
	s_addc_u32 s23, s97, 0
	s_add_u32 s24, s96, 0x4d00
	s_addc_u32 s25, s97, 0
	s_add_u32 s26, s96, 0x4e00
	s_addc_u32 s27, s97, 0
	s_add_u32 s28, s96, 0x4f00
	s_addc_u32 s29, s97, 0
	s_add_u32 s30, s96, 0x5000
	s_addc_u32 s31, s97, 0
	s_add_u32 s34, s96, 0x5100
	s_addc_u32 s35, s97, 0
	s_add_u32 s36, s96, 0x5200
	s_addc_u32 s37, s97, 0
	s_add_u32 s38, s96, 0x5300
	s_addc_u32 s39, s97, 0
	s_mov_b32 s46, 1
	v_mov_b32_e32 v17, 0
	s_branch .LBB0_632
